# FFN1 epilogue no longer waits on vmcnt(0) (prefetched rstd retired by K-loop counted waits), so it does not stall behind the next unit's DMA prefetch
# baseline (speedup 1.0000x reference)
.LBB0_1498:
	v_mov_b32_e32 v153, v146
	s_lshl_b32 s0, s63, 8
	s_add_i32 s0, s0, s53
	v_add_u32_e32 v142, s0, v147
	v_ashrrev_i32_e32 v143, 31, v142
	s_cmp_lg_u32 s101, 0
	s_cbranch_scc1 .Lf1_have
	v_lshl_add_u64 v[144:145], v[142:143], 2, s[18:19]
	global_load_dword v240, v[144:145], off
	global_load_dword v241, v[144:145], off offset:64
	global_load_dword v242, v[144:145], off offset:128
	global_load_dword v243, v[144:145], off offset:192
	global_load_dword v244, v[144:145], off offset:512
	global_load_dword v245, v[144:145], off offset:576
	global_load_dword v246, v[144:145], off offset:640
	global_load_dword v247, v[144:145], off offset:704
	s_mov_b32 s101, 1
	s_waitcnt vmcnt(0)
.Lf1_have:
	s_lshl_b32 s0, s62, 7
	s_or_b32 s0, s0, s54
	v_lshl_add_u32 v156, v153, 3, s0
	v_ashrrev_i32_e32 v157, 31, v156
	v_mov_b64_e32 v[162:163], s[10:11]
	v_mad_i64_i32 v[160:161], s[0:1], v142, s59, v[162:163]
	v_lshlrev_b64 v[162:163], 1, v[156:157]
	v_lshl_add_u64 v[160:161], v[160:161], 0, v[162:163]
	v_mov_b32_e32 v164, 1.0
	v_mov_b32_e32 v165, 1.0
	s_lshl_b32 s0, s61, 8
	s_add_i32 s0, s0, s53
	v_add_u32_e32 v144, s0, v147
	v_ashrrev_i32_e32 v145, 31, v144
	v_lshl_add_u64 v[144:145], v[144:145], 2, s[18:19]
	v_mov_b32_e32 v152, v240
	v_mov_b32_e32 v233, v241
	v_mov_b32_e32 v234, v242
	v_mov_b32_e32 v235, v243
	v_mov_b32_e32 v236, v244
	v_mov_b32_e32 v237, v245
	v_mov_b32_e32 v238, v246
	v_mov_b32_e32 v239, v247
	global_load_dword v240, v[144:145], off
	global_load_dword v241, v[144:145], off offset:64
	global_load_dword v242, v[144:145], off offset:128
	global_load_dword v243, v[144:145], off offset:192
	global_load_dword v244, v[144:145], off offset:512
	global_load_dword v245, v[144:145], off offset:576
	global_load_dword v246, v[144:145], off offset:640
	global_load_dword v247, v[144:145], off offset:704
	v_mul_f32_e32 v166, 0xbfb8aa3b, v152
	v_mul_f32_e32 v168, v152, v152
	v_pk_mul_f32 v[170:171], v[120:121], v[166:167] op_sel_hi:[1,0]
	v_pk_mul_f32 v[172:173], v[122:123], v[166:167] op_sel_hi:[1,0]
	v_pk_mul_f32 v[174:175], v[112:113], v[166:167] op_sel_hi:[1,0]
	v_pk_mul_f32 v[176:177], v[114:115], v[166:167] op_sel_hi:[1,0]
	v_pk_mul_f32 v[178:179], v[120:121], v[124:125]
	v_pk_mul_f32 v[180:181], v[122:123], v[126:127]
	v_pk_mul_f32 v[182:183], v[112:113], v[116:117]
	v_pk_mul_f32 v[184:185], v[114:115], v[118:119]
	v_exp_f32_e32 v170, v170
	v_exp_f32_e32 v171, v171
	v_exp_f32_e32 v172, v172
	v_exp_f32_e32 v173, v173
	v_exp_f32_e32 v174, v174
	v_exp_f32_e32 v175, v175
	v_exp_f32_e32 v176, v176
	v_exp_f32_e32 v177, v177
	s_nop 0
	v_pk_add_f32 v[170:171], v[170:171], v[164:165]
	v_pk_add_f32 v[172:173], v[172:173], v[164:165]
	v_pk_add_f32 v[174:175], v[174:175], v[164:165]
	v_pk_add_f32 v[176:177], v[176:177], v[164:165]
	v_rcp_f32_e32 v170, v170
	v_rcp_f32_e32 v171, v171
	v_rcp_f32_e32 v172, v172
	v_rcp_f32_e32 v173, v173
	v_rcp_f32_e32 v174, v174
	v_rcp_f32_e32 v175, v175
	v_rcp_f32_e32 v176, v176
	v_rcp_f32_e32 v177, v177
	s_nop 0
	v_pk_mul_f32 v[170:171], v[170:171], v[168:169] op_sel_hi:[1,0]
	v_pk_mul_f32 v[172:173], v[172:173], v[168:169] op_sel_hi:[1,0]
	v_pk_mul_f32 v[174:175], v[174:175], v[168:169] op_sel_hi:[1,0]
	v_pk_mul_f32 v[176:177], v[176:177], v[168:169] op_sel_hi:[1,0]
	v_pk_mul_f32 v[178:179], v[178:179], v[170:171]
	v_pk_mul_f32 v[180:181], v[180:181], v[172:173]
	v_pk_mul_f32 v[182:183], v[182:183], v[174:175]
	v_pk_mul_f32 v[184:185], v[184:185], v[176:177]
	v_cvt_pk_bf16_f32 v186, v178, v179
	v_cvt_pk_bf16_f32 v187, v180, v181
	v_cvt_pk_bf16_f32 v188, v182, v183
	v_cvt_pk_bf16_f32 v189, v184, v185
	global_store_dwordx4 v[160:161], v[186:189], off
	s_nop 1
	s_mov_b64 s[98:99], 0x2c000
	v_lshl_add_u64 v[160:161], v[160:161], 0, s[98:99]
	v_mul_f32_e32 v166, 0xbfb8aa3b, v233
	v_mul_f32_e32 v168, v233, v233
	v_pk_mul_f32 v[170:171], v[104:105], v[166:167] op_sel_hi:[1,0]
	v_pk_mul_f32 v[172:173], v[106:107], v[166:167] op_sel_hi:[1,0]
	v_pk_mul_f32 v[174:175], v[96:97], v[166:167] op_sel_hi:[1,0]
	v_pk_mul_f32 v[176:177], v[98:99], v[166:167] op_sel_hi:[1,0]
	v_pk_mul_f32 v[178:179], v[104:105], v[108:109]
	v_pk_mul_f32 v[180:181], v[106:107], v[110:111]
	v_pk_mul_f32 v[182:183], v[96:97], v[100:101]
	v_pk_mul_f32 v[184:185], v[98:99], v[102:103]
	v_exp_f32_e32 v170, v170
	v_exp_f32_e32 v171, v171
	v_exp_f32_e32 v172, v172
	v_exp_f32_e32 v173, v173
	v_exp_f32_e32 v174, v174
	v_exp_f32_e32 v175, v175
	v_exp_f32_e32 v176, v176
	v_exp_f32_e32 v177, v177
	s_nop 0
	v_pk_add_f32 v[170:171], v[170:171], v[164:165]
	v_pk_add_f32 v[172:173], v[172:173], v[164:165]
	v_pk_add_f32 v[174:175], v[174:175], v[164:165]
	v_pk_add_f32 v[176:177], v[176:177], v[164:165]
	v_rcp_f32_e32 v170, v170
	v_rcp_f32_e32 v171, v171
	v_rcp_f32_e32 v172, v172
	v_rcp_f32_e32 v173, v173
	v_rcp_f32_e32 v174, v174
	v_rcp_f32_e32 v175, v175
	v_rcp_f32_e32 v176, v176
	v_rcp_f32_e32 v177, v177
	s_nop 0
	v_pk_mul_f32 v[170:171], v[170:171], v[168:169] op_sel_hi:[1,0]
	v_pk_mul_f32 v[172:173], v[172:173], v[168:169] op_sel_hi:[1,0]
	v_pk_mul_f32 v[174:175], v[174:175], v[168:169] op_sel_hi:[1,0]
	v_pk_mul_f32 v[176:177], v[176:177], v[168:169] op_sel_hi:[1,0]
	v_pk_mul_f32 v[178:179], v[178:179], v[170:171]
	v_pk_mul_f32 v[180:181], v[180:181], v[172:173]
	v_pk_mul_f32 v[182:183], v[182:183], v[174:175]
	v_pk_mul_f32 v[184:185], v[184:185], v[176:177]
	v_cvt_pk_bf16_f32 v186, v178, v179
	v_cvt_pk_bf16_f32 v187, v180, v181
	v_cvt_pk_bf16_f32 v188, v182, v183
	v_cvt_pk_bf16_f32 v189, v184, v185
	global_store_dwordx4 v[160:161], v[186:189], off
	s_nop 1
	s_mov_b64 s[98:99], 0x2c000
	v_lshl_add_u64 v[160:161], v[160:161], 0, s[98:99]
	v_mul_f32_e32 v166, 0xbfb8aa3b, v234
	v_mul_f32_e32 v168, v234, v234
	v_pk_mul_f32 v[170:171], v[88:89], v[166:167] op_sel_hi:[1,0]
	v_pk_mul_f32 v[172:173], v[90:91], v[166:167] op_sel_hi:[1,0]
	v_pk_mul_f32 v[174:175], v[80:81], v[166:167] op_sel_hi:[1,0]
	v_pk_mul_f32 v[176:177], v[82:83], v[166:167] op_sel_hi:[1,0]
	v_pk_mul_f32 v[178:179], v[88:89], v[92:93]
	v_pk_mul_f32 v[180:181], v[90:91], v[94:95]
	v_pk_mul_f32 v[182:183], v[80:81], v[84:85]
	v_pk_mul_f32 v[184:185], v[82:83], v[86:87]
	v_exp_f32_e32 v170, v170
	v_exp_f32_e32 v171, v171
	v_exp_f32_e32 v172, v172
	v_exp_f32_e32 v173, v173
	v_exp_f32_e32 v174, v174
	v_exp_f32_e32 v175, v175
	v_exp_f32_e32 v176, v176
	v_exp_f32_e32 v177, v177
	s_nop 0
	v_pk_add_f32 v[170:171], v[170:171], v[164:165]
	v_pk_add_f32 v[172:173], v[172:173], v[164:165]
	v_pk_add_f32 v[174:175], v[174:175], v[164:165]
	v_pk_add_f32 v[176:177], v[176:177], v[164:165]
	v_rcp_f32_e32 v170, v170
	v_rcp_f32_e32 v171, v171
	v_rcp_f32_e32 v172, v172
	v_rcp_f32_e32 v173, v173
	v_rcp_f32_e32 v174, v174
	v_rcp_f32_e32 v175, v175
	v_rcp_f32_e32 v176, v176
	v_rcp_f32_e32 v177, v177
	s_nop 0
	v_pk_mul_f32 v[170:171], v[170:171], v[168:169] op_sel_hi:[1,0]
	v_pk_mul_f32 v[172:173], v[172:173], v[168:169] op_sel_hi:[1,0]
	v_pk_mul_f32 v[174:175], v[174:175], v[168:169] op_sel_hi:[1,0]
	v_pk_mul_f32 v[176:177], v[176:177], v[168:169] op_sel_hi:[1,0]
	v_pk_mul_f32 v[178:179], v[178:179], v[170:171]
	v_pk_mul_f32 v[180:181], v[180:181], v[172:173]
	v_pk_mul_f32 v[182:183], v[182:183], v[174:175]
	v_pk_mul_f32 v[184:185], v[184:185], v[176:177]
	v_cvt_pk_bf16_f32 v186, v178, v179
	v_cvt_pk_bf16_f32 v187, v180, v181
	v_cvt_pk_bf16_f32 v188, v182, v183
	v_cvt_pk_bf16_f32 v189, v184, v185
	global_store_dwordx4 v[160:161], v[186:189], off
	s_nop 1
	s_mov_b64 s[98:99], 0x2c000
	v_lshl_add_u64 v[160:161], v[160:161], 0, s[98:99]
	v_mul_f32_e32 v166, 0xbfb8aa3b, v235
	v_mul_f32_e32 v168, v235, v235
	v_pk_mul_f32 v[170:171], v[72:73], v[166:167] op_sel_hi:[1,0]
	v_pk_mul_f32 v[172:173], v[74:75], v[166:167] op_sel_hi:[1,0]
	v_pk_mul_f32 v[174:175], v[64:65], v[166:167] op_sel_hi:[1,0]
	v_pk_mul_f32 v[176:177], v[66:67], v[166:167] op_sel_hi:[1,0]
	v_pk_mul_f32 v[178:179], v[72:73], v[76:77]
	v_pk_mul_f32 v[180:181], v[74:75], v[78:79]
	v_pk_mul_f32 v[182:183], v[64:65], v[68:69]
	v_pk_mul_f32 v[184:185], v[66:67], v[70:71]
	v_exp_f32_e32 v170, v170
	v_exp_f32_e32 v171, v171
	v_exp_f32_e32 v172, v172
	v_exp_f32_e32 v173, v173
	v_exp_f32_e32 v174, v174
	v_exp_f32_e32 v175, v175
	v_exp_f32_e32 v176, v176
	v_exp_f32_e32 v177, v177
	s_nop 0
	v_pk_add_f32 v[170:171], v[170:171], v[164:165]
	v_pk_add_f32 v[172:173], v[172:173], v[164:165]
	v_pk_add_f32 v[174:175], v[174:175], v[164:165]
	v_pk_add_f32 v[176:177], v[176:177], v[164:165]
	v_rcp_f32_e32 v170, v170
	v_rcp_f32_e32 v171, v171
	v_rcp_f32_e32 v172, v172
	v_rcp_f32_e32 v173, v173
	v_rcp_f32_e32 v174, v174
	v_rcp_f32_e32 v175, v175
	v_rcp_f32_e32 v176, v176
	v_rcp_f32_e32 v177, v177
	s_nop 0
	v_pk_mul_f32 v[170:171], v[170:171], v[168:169] op_sel_hi:[1,0]
	v_pk_mul_f32 v[172:173], v[172:173], v[168:169] op_sel_hi:[1,0]
	v_pk_mul_f32 v[174:175], v[174:175], v[168:169] op_sel_hi:[1,0]
	v_pk_mul_f32 v[176:177], v[176:177], v[168:169] op_sel_hi:[1,0]
	v_pk_mul_f32 v[178:179], v[178:179], v[170:171]
	v_pk_mul_f32 v[180:181], v[180:181], v[172:173]
	v_pk_mul_f32 v[182:183], v[182:183], v[174:175]
	v_pk_mul_f32 v[184:185], v[184:185], v[176:177]
	v_cvt_pk_bf16_f32 v186, v178, v179
	v_cvt_pk_bf16_f32 v187, v180, v181
	v_cvt_pk_bf16_f32 v188, v182, v183
	v_cvt_pk_bf16_f32 v189, v184, v185
	global_store_dwordx4 v[160:161], v[186:189], off
	s_nop 1
	s_mov_b64 s[98:99], 0xdc000
	v_lshl_add_u64 v[160:161], v[160:161], 0, s[98:99]
	v_mul_f32_e32 v166, 0xbfb8aa3b, v236
	v_mul_f32_e32 v168, v236, v236
	v_pk_mul_f32 v[170:171], v[56:57], v[166:167] op_sel_hi:[1,0]
	v_pk_mul_f32 v[172:173], v[58:59], v[166:167] op_sel_hi:[1,0]
	v_pk_mul_f32 v[174:175], v[48:49], v[166:167] op_sel_hi:[1,0]
	v_pk_mul_f32 v[176:177], v[50:51], v[166:167] op_sel_hi:[1,0]
	v_pk_mul_f32 v[178:179], v[56:57], v[60:61]
	v_pk_mul_f32 v[180:181], v[58:59], v[62:63]
	v_pk_mul_f32 v[182:183], v[48:49], v[52:53]
	v_pk_mul_f32 v[184:185], v[50:51], v[54:55]
	v_exp_f32_e32 v170, v170
	v_exp_f32_e32 v171, v171
	v_exp_f32_e32 v172, v172
	v_exp_f32_e32 v173, v173
	v_exp_f32_e32 v174, v174
	v_exp_f32_e32 v175, v175
	v_exp_f32_e32 v176, v176
	v_exp_f32_e32 v177, v177
	s_nop 0
	v_pk_add_f32 v[170:171], v[170:171], v[164:165]
	v_pk_add_f32 v[172:173], v[172:173], v[164:165]
	v_pk_add_f32 v[174:175], v[174:175], v[164:165]
	v_pk_add_f32 v[176:177], v[176:177], v[164:165]
	v_rcp_f32_e32 v170, v170
	v_rcp_f32_e32 v171, v171
	v_rcp_f32_e32 v172, v172
	v_rcp_f32_e32 v173, v173
	v_rcp_f32_e32 v174, v174
	v_rcp_f32_e32 v175, v175
	v_rcp_f32_e32 v176, v176
	v_rcp_f32_e32 v177, v177
	s_nop 0
	v_pk_mul_f32 v[170:171], v[170:171], v[168:169] op_sel_hi:[1,0]
	v_pk_mul_f32 v[172:173], v[172:173], v[168:169] op_sel_hi:[1,0]
	v_pk_mul_f32 v[174:175], v[174:175], v[168:169] op_sel_hi:[1,0]
	v_pk_mul_f32 v[176:177], v[176:177], v[168:169] op_sel_hi:[1,0]
	v_pk_mul_f32 v[178:179], v[178:179], v[170:171]
	v_pk_mul_f32 v[180:181], v[180:181], v[172:173]
	v_pk_mul_f32 v[182:183], v[182:183], v[174:175]
	v_pk_mul_f32 v[184:185], v[184:185], v[176:177]
	v_cvt_pk_bf16_f32 v186, v178, v179
	v_cvt_pk_bf16_f32 v187, v180, v181
	v_cvt_pk_bf16_f32 v188, v182, v183
	v_cvt_pk_bf16_f32 v189, v184, v185
	global_store_dwordx4 v[160:161], v[186:189], off
	s_nop 1
	s_mov_b64 s[98:99], 0x2c000
	v_lshl_add_u64 v[160:161], v[160:161], 0, s[98:99]
	v_mul_f32_e32 v166, 0xbfb8aa3b, v237
	v_mul_f32_e32 v168, v237, v237
	v_pk_mul_f32 v[170:171], v[40:41], v[166:167] op_sel_hi:[1,0]
	v_pk_mul_f32 v[172:173], v[42:43], v[166:167] op_sel_hi:[1,0]
	v_pk_mul_f32 v[174:175], v[32:33], v[166:167] op_sel_hi:[1,0]
	v_pk_mul_f32 v[176:177], v[34:35], v[166:167] op_sel_hi:[1,0]
	v_pk_mul_f32 v[178:179], v[40:41], v[44:45]
	v_pk_mul_f32 v[180:181], v[42:43], v[46:47]
	v_pk_mul_f32 v[182:183], v[32:33], v[36:37]
	v_pk_mul_f32 v[184:185], v[34:35], v[38:39]
	v_exp_f32_e32 v170, v170
	v_exp_f32_e32 v171, v171
	v_exp_f32_e32 v172, v172
	v_exp_f32_e32 v173, v173
	v_exp_f32_e32 v174, v174
	v_exp_f32_e32 v175, v175
	v_exp_f32_e32 v176, v176
	v_exp_f32_e32 v177, v177
	s_nop 0
	v_pk_add_f32 v[170:171], v[170:171], v[164:165]
	v_pk_add_f32 v[172:173], v[172:173], v[164:165]
	v_pk_add_f32 v[174:175], v[174:175], v[164:165]
	v_pk_add_f32 v[176:177], v[176:177], v[164:165]
	v_rcp_f32_e32 v170, v170
	v_rcp_f32_e32 v171, v171
	v_rcp_f32_e32 v172, v172
	v_rcp_f32_e32 v173, v173
	v_rcp_f32_e32 v174, v174
	v_rcp_f32_e32 v175, v175
	v_rcp_f32_e32 v176, v176
	v_rcp_f32_e32 v177, v177
	s_nop 0
	v_pk_mul_f32 v[170:171], v[170:171], v[168:169] op_sel_hi:[1,0]
	v_pk_mul_f32 v[172:173], v[172:173], v[168:169] op_sel_hi:[1,0]
	v_pk_mul_f32 v[174:175], v[174:175], v[168:169] op_sel_hi:[1,0]
	v_pk_mul_f32 v[176:177], v[176:177], v[168:169] op_sel_hi:[1,0]
	v_pk_mul_f32 v[178:179], v[178:179], v[170:171]
	v_pk_mul_f32 v[180:181], v[180:181], v[172:173]
	v_pk_mul_f32 v[182:183], v[182:183], v[174:175]
	v_pk_mul_f32 v[184:185], v[184:185], v[176:177]
	v_cvt_pk_bf16_f32 v186, v178, v179
	v_cvt_pk_bf16_f32 v187, v180, v181
	v_cvt_pk_bf16_f32 v188, v182, v183
	v_cvt_pk_bf16_f32 v189, v184, v185
	global_store_dwordx4 v[160:161], v[186:189], off
	s_nop 1
	s_mov_b64 s[98:99], 0x2c000
	v_lshl_add_u64 v[160:161], v[160:161], 0, s[98:99]
	v_mul_f32_e32 v166, 0xbfb8aa3b, v238
	v_mul_f32_e32 v168, v238, v238
	v_pk_mul_f32 v[170:171], v[24:25], v[166:167] op_sel_hi:[1,0]
	v_pk_mul_f32 v[172:173], v[26:27], v[166:167] op_sel_hi:[1,0]
	v_pk_mul_f32 v[174:175], v[16:17], v[166:167] op_sel_hi:[1,0]
	v_pk_mul_f32 v[176:177], v[18:19], v[166:167] op_sel_hi:[1,0]
	v_pk_mul_f32 v[178:179], v[24:25], v[28:29]
	v_pk_mul_f32 v[180:181], v[26:27], v[30:31]
	v_pk_mul_f32 v[182:183], v[16:17], v[20:21]
	v_pk_mul_f32 v[184:185], v[18:19], v[22:23]
	v_exp_f32_e32 v170, v170
	v_exp_f32_e32 v171, v171
	v_exp_f32_e32 v172, v172
	v_exp_f32_e32 v173, v173
	v_exp_f32_e32 v174, v174
	v_exp_f32_e32 v175, v175
	v_exp_f32_e32 v176, v176
	v_exp_f32_e32 v177, v177
	s_nop 0
	v_pk_add_f32 v[170:171], v[170:171], v[164:165]
	v_pk_add_f32 v[172:173], v[172:173], v[164:165]
	v_pk_add_f32 v[174:175], v[174:175], v[164:165]
	v_pk_add_f32 v[176:177], v[176:177], v[164:165]
	v_rcp_f32_e32 v170, v170
	v_rcp_f32_e32 v171, v171
	v_rcp_f32_e32 v172, v172
	v_rcp_f32_e32 v173, v173
	v_rcp_f32_e32 v174, v174
	v_rcp_f32_e32 v175, v175
	v_rcp_f32_e32 v176, v176
	v_rcp_f32_e32 v177, v177
	s_nop 0
	v_pk_mul_f32 v[170:171], v[170:171], v[168:169] op_sel_hi:[1,0]
	v_pk_mul_f32 v[172:173], v[172:173], v[168:169] op_sel_hi:[1,0]
	v_pk_mul_f32 v[174:175], v[174:175], v[168:169] op_sel_hi:[1,0]
	v_pk_mul_f32 v[176:177], v[176:177], v[168:169] op_sel_hi:[1,0]
	v_pk_mul_f32 v[178:179], v[178:179], v[170:171]
	v_pk_mul_f32 v[180:181], v[180:181], v[172:173]
	v_pk_mul_f32 v[182:183], v[182:183], v[174:175]
	v_pk_mul_f32 v[184:185], v[184:185], v[176:177]
	v_cvt_pk_bf16_f32 v186, v178, v179
	v_cvt_pk_bf16_f32 v187, v180, v181
	v_cvt_pk_bf16_f32 v188, v182, v183
	v_cvt_pk_bf16_f32 v189, v184, v185
	global_store_dwordx4 v[160:161], v[186:189], off
	s_nop 1
	s_mov_b64 s[98:99], 0x2c000
	v_lshl_add_u64 v[160:161], v[160:161], 0, s[98:99]
	v_mul_f32_e32 v166, 0xbfb8aa3b, v239
	v_mul_f32_e32 v168, v239, v239
	v_pk_mul_f32 v[170:171], v[8:9], v[166:167] op_sel_hi:[1,0]
	v_pk_mul_f32 v[172:173], v[10:11], v[166:167] op_sel_hi:[1,0]
	v_pk_mul_f32 v[174:175], v[4:5], v[166:167] op_sel_hi:[1,0]
	v_pk_mul_f32 v[176:177], v[6:7], v[166:167] op_sel_hi:[1,0]
	v_pk_mul_f32 v[178:179], v[8:9], v[12:13]
	v_pk_mul_f32 v[180:181], v[10:11], v[14:15]
	v_pk_mul_f32 v[182:183], v[4:5], v[0:1]
	v_pk_mul_f32 v[184:185], v[6:7], v[2:3]
	v_exp_f32_e32 v170, v170
	v_exp_f32_e32 v171, v171
	v_exp_f32_e32 v172, v172
	v_exp_f32_e32 v173, v173
	v_exp_f32_e32 v174, v174
	v_exp_f32_e32 v175, v175
	v_exp_f32_e32 v176, v176
	v_exp_f32_e32 v177, v177
	s_nop 0
	v_pk_add_f32 v[170:171], v[170:171], v[164:165]
	v_pk_add_f32 v[172:173], v[172:173], v[164:165]
	v_pk_add_f32 v[174:175], v[174:175], v[164:165]
	v_pk_add_f32 v[176:177], v[176:177], v[164:165]
	v_rcp_f32_e32 v170, v170
	v_rcp_f32_e32 v171, v171
	v_rcp_f32_e32 v172, v172
	v_rcp_f32_e32 v173, v173
	v_rcp_f32_e32 v174, v174
	v_rcp_f32_e32 v175, v175
	v_rcp_f32_e32 v176, v176
	v_rcp_f32_e32 v177, v177
	s_nop 0
	v_pk_mul_f32 v[170:171], v[170:171], v[168:169] op_sel_hi:[1,0]
	v_pk_mul_f32 v[172:173], v[172:173], v[168:169] op_sel_hi:[1,0]
	v_pk_mul_f32 v[174:175], v[174:175], v[168:169] op_sel_hi:[1,0]
	v_pk_mul_f32 v[176:177], v[176:177], v[168:169] op_sel_hi:[1,0]
	v_pk_mul_f32 v[178:179], v[178:179], v[170:171]
	v_pk_mul_f32 v[180:181], v[180:181], v[172:173]
	v_pk_mul_f32 v[182:183], v[182:183], v[174:175]
	v_pk_mul_f32 v[184:185], v[184:185], v[176:177]
	v_cvt_pk_bf16_f32 v186, v178, v179
	v_cvt_pk_bf16_f32 v187, v180, v181
	v_cvt_pk_bf16_f32 v188, v182, v183
	v_cvt_pk_bf16_f32 v189, v184, v185
	s_and_b64 vcc, exec, s[2:3]
	s_mov_b64 s[2:3], -1
	global_store_dwordx4 v[160:161], v[186:189], off
	s_cbranch_vccnz .LBB0_1486
	s_andn2_b64 vcc, exec, s[16:17]
	s_cbranch_vccnz .LBB0_1485
	s_barrier
	s_branch .LBB0_1485
